# v44 plus counted LDS waits in the attention-B post-loop tail tile (waits to first consumer)
# speedup vs baseline: 1.0186x; 1.0005x over previous
; #define WBAR(n) do { asm volatile("s_waitcnt vmcnt(" #n ") lgkmcnt(0)" ::: "memory"); __builtin_amdgcn_s_barrier(); asm volatile("" ::: "memory"); } while (0)
; #define WBAR(n) do { asm volatile("s_waitcnt vmcnt(" #n ") lgkmcnt(0)" ::: "memory"); __builtin_amdgcn_s_barrier(); asm volatile("" ::: "memory"); } while (0)
; template <int LD> ...
;     ...
;   STEP(1, pB, ownA0, ownA1, ownB0, ownB1);
;   WBAR(0);
.Lb_loop_done:
	ds_read_b128 v[84:87], v171 offset:0
	ds_read_b128 v[80:83], v171 offset:0x400
	v_add_u32_e32 v179, s25, v217
	ds_read_b64_tr_b16 v[88:89], v179 offset:0
	ds_read_b64_tr_b16 v[90:91], v179 offset:0x800
	ds_read_b64_tr_b16 v[92:93], v179 offset:0x1000
	ds_read_b64_tr_b16 v[94:95], v179 offset:0x1800
	v_add_u32_e32 v151, s25, v151
	ds_read_b64_tr_b16 v[136:137], v151 offset:0
	ds_read_b64_tr_b16 v[138:139], v151 offset:0x800
	ds_read_b64_tr_b16 v[140:141], v151 offset:0x1000
	ds_read_b64_tr_b16 v[142:143], v151 offset:0x1800
	v_xad_u32 v180, v172, v178, v173
	ds_read_b128 v[144:147], v180 offset:0x4000
	v_xad_u32 v174, v172, v174, v173
	ds_read_b128 v[152:155], v174 offset:0x4000
	v_xad_u32 v175, v172, v175, v173
	ds_read_b128 v[156:159], v175 offset:0x4000
	v_xad_u32 v172, v172, v176, v173
	ds_read_b128 v[166:169], v172 offset:0x4000
	v_cmp_gt_u32_e32 vcc, 32, v150
	s_waitcnt lgkmcnt(3)
	v_mfma_f32_32x32x16_bf16 v[64:79], v[144:147], v[120:123], v[64:79]
	s_waitcnt lgkmcnt(2)
	v_mfma_f32_32x32x16_bf16 v[64:79], v[152:155], v[124:127], v[64:79]
	s_waitcnt lgkmcnt(1)
	v_mfma_f32_32x32x16_bf16 v[64:79], v[156:159], v[112:115], v[64:79]
	v_mfma_f32_32x32x16_bf16 v[48:63], v[128:131], v[88:91], v[48:63]
	v_xor_b32_e32 v180, 0x80, v180
	ds_read_b128 v[88:91], v180 offset:0x4000
	v_xor_b32_e32 v180, 0x80, v180
	v_xor_b32_e32 v174, 0x80, v174
	ds_read_b128 v[120:123], v174 offset:0x4000
	v_xor_b32_e32 v174, 0x80, v174
	v_xor_b32_e32 v175, 0x80, v175
	ds_read_b128 v[112:115], v175 offset:0x4000
	v_xor_b32_e32 v175, 0x80, v175
	v_xor_b32_e32 v172, 0x80, v172
	ds_read_b128 v[124:127], v172 offset:0x4000
	v_xor_b32_e32 v172, 0x80, v172
	ds_read_b64_tr_b16 v[144:145], v179 offset:0x200
	ds_read_b64_tr_b16 v[146:147], v179 offset:0xa00
	ds_read_b64_tr_b16 v[152:153], v179 offset:0x1200
	ds_read_b64_tr_b16 v[154:155], v179 offset:0x1a00
	s_waitcnt lgkmcnt(8)
	v_mfma_f32_32x32x16_bf16 v[64:79], v[166:169], v[100:103], v[64:79]
	ds_read_b64_tr_b16 v[156:157], v151 offset:0x200
	ds_read_b64_tr_b16 v[158:159], v151 offset:0xa00
	ds_read_b64_tr_b16 v[100:101], v151 offset:0x1200
	ds_read_b64_tr_b16 v[102:103], v151 offset:0x1a00
	v_mfma_f32_32x32x16_bf16 v[48:63], v[132:135], v[92:95], v[48:63]
	s_waitcnt lgkmcnt(11)
	v_mfma_f32_32x32x16_bf16 v[64:79], v[88:91], v[96:99], v[64:79]
	ds_read_b64_tr_b16 v[88:89], v179 offset:0x400
	ds_read_b64_tr_b16 v[90:91], v179 offset:0xc00
	ds_read_b64_tr_b16 v[92:93], v179 offset:0x1400
	ds_read_b64_tr_b16 v[94:95], v179 offset:0x1c00
	s_waitcnt lgkmcnt(14)
	ds_read_b64_tr_b16 v[96:97], v151 offset:0x400
	s_waitcnt lgkmcnt(14)
	ds_read_b64_tr_b16 v[98:99], v151 offset:0xc00
	s_waitcnt lgkmcnt(12)
	v_mfma_f32_32x32x16_bf16 v[32:47], v[128:131], v[144:147], v[32:47]
	v_mfma_f32_32x32x16_bf16 v[64:79], v[120:123], v[104:107], v[64:79]
	ds_read_b64_tr_b16 v[104:105], v151 offset:0x1400
	ds_read_b64_tr_b16 v[106:107], v151 offset:0x1c00
	s_nop 0
	s_nop 0
	s_waitcnt lgkmcnt(6)
	v_mfma_f32_32x32x16_bf16 v[16:31], v[128:131], v[88:91], v[16:31]
	ds_read_b64_tr_b16 v[88:89], v179 offset:0x600
	ds_read_b64_tr_b16 v[90:91], v179 offset:0xe00
	v_mfma_f32_32x32x16_bf16 v[32:47], v[132:135], v[152:155], v[32:47]
	s_waitcnt lgkmcnt(6)
	v_mfma_f32_32x32x16_bf16 v[16:31], v[132:135], v[92:95], v[16:31]
	ds_read_b64_tr_b16 v[92:93], v179 offset:0x1600
	ds_read_b64_tr_b16 v[94:95], v179 offset:0x1e00
	v_mfma_f32_32x32x16_bf16 v[32:47], v[84:87], v[156:159], v[32:47]
	s_waitcnt lgkmcnt(6)
	v_mfma_f32_32x32x16_bf16 v[16:31], v[84:87], v[96:99], v[16:31]
	ds_read_b64_tr_b16 v[96:97], v151 offset:0x600
	ds_read_b64_tr_b16 v[98:99], v151 offset:0xe00
	v_mfma_f32_32x32x16_bf16 v[32:47], v[80:83], v[100:103], v[32:47]
	ds_read_b64_tr_b16 v[100:101], v151 offset:0x1600
	ds_read_b64_tr_b16 v[102:103], v151 offset:0x1e00
	s_nop 0
	s_nop 0
	s_waitcnt lgkmcnt(6)
	v_mfma_f32_32x32x16_bf16 v[0:15], v[128:131], v[88:91], v[0:15]
	v_mfma_f32_32x32x16_bf16 v[64:79], v[112:115], v[108:111], v[64:79]
	s_waitcnt lgkmcnt(4)
	v_mfma_f32_32x32x16_bf16 v[0:15], v[132:135], v[92:95], v[0:15]
	v_mfma_f32_32x32x16_bf16 v[64:79], v[124:127], v[116:119], v[64:79]
	s_waitcnt lgkmcnt(2)
	v_mfma_f32_32x32x16_bf16 v[0:15], v[84:87], v[96:99], v[0:15]
	s_nop 10
	v_exp_f32_e32 v108, v68
	v_exp_f32_e32 v109, v69
	v_exp_f32_e32 v110, v70
	v_exp_f32_e32 v111, v71
	v_exp_f32_e32 v112, v72
	v_exp_f32_e32 v113, v73
	v_exp_f32_e32 v114, v74
	v_mfma_f32_32x32x16_bf16 v[16:31], v[80:83], v[104:107], v[16:31]
	v_exp_f32_e32 v104, v64
	v_exp_f32_e32 v105, v65
	v_exp_f32_e32 v106, v66
	v_exp_f32_e32 v107, v67
	v_exp_f32_e32 v115, v75
	v_cvt_pk_bf16_f32 v64, v104, v105
	v_cvt_pk_bf16_f32 v66, v108, v109
	v_mfma_f32_32x32x16_bf16 v[48:63], v[84:87], v[136:139], v[48:63]
	v_cvt_pk_bf16_f32 v65, v106, v107
	v_cvt_pk_bf16_f32 v67, v110, v111
	v_cvt_pk_bf16_f32 v68, v112, v113
	v_cvt_pk_bf16_f32 v69, v114, v115
	s_waitcnt lgkmcnt(0)
	v_mfma_f32_32x32x16_bf16 v[0:15], v[80:83], v[100:103], v[0:15]
	v_exp_f32_e32 v100, v76
	v_exp_f32_e32 v101, v77
	v_exp_f32_e32 v102, v78
	v_exp_f32_e32 v103, v79
	v_cvt_pk_bf16_f32 v70, v100, v101
	v_cvt_pk_bf16_f32 v71, v102, v103
	ds_write_b128 v181, v[64:67]
	ds_write_b128 v181, v[68:71] offset:1024
	s_waitcnt vmcnt(0) lgkmcnt(0)
	s_barrier
; __device__ __forceinline__ int crow(int r, int hi) { return (r & 3) + 8 * (r >> 2) + 4 * hi; }
; #define WBAR(n) do { asm volatile("s_waitcnt vmcnt(" #n ") lgkmcnt(0)" ::: "memory"); __builtin_amdgcn_s_barrier(); asm volatile("" ::: "memory"); } while (0)
; #define TRB(T, D0, vo_, vt_) do { T[0] = tr_read<v_rd_off(D0, 0, 0)>(vo_); T[1] = tr_read<v_rd_off(D0, 0, 1)>(vo_); T[2] = tr_read<v_rd_off(D0, 1, 0)>(vo_); T[3] = tr_read<v_rd_off(D0, 1, 1)>(vo_); \
;     T[4] = tr_read<v_rd_off(D0, 0, 0)>(vt_); T[5] = tr_read<v_rd_off(D0, 0, 1)>(vt_); T[6] = tr_read<v_rd_off(D0, 1, 0)>(vt_); T[7] = tr_read<v_rd_off(D0, 1, 1)>(vt_); } while (0)
; #define TRW(T, n) asm volatile("s_waitcnt lgkmcnt(" #n ")" : "+v"(T[0]), "+v"(T[1]), "+v"(T[2]), "+v"(T[3]), "+v"(T[4]), "+v"(T[5]), "+v"(T[6]), "+v"(T[7]) :: "memory")
; #define MB(od, T, o0, o1, t0, t1) do { od = __builtin_amdgcn_mfma_f32_32x32x16_bf16(o0, PKV(T[0], T[1]), od, 0, 0, 0); od = __builtin_amdgcn_mfma_f32_32x32x16_bf16(o1, PKV(T[2], T[3]), od, 0, 0, 0); \
;     od = __builtin_amdgcn_mfma_f32_32x32x16_bf16(t0, PKV(T[4], T[5]), od, 0, 0, 0); od = __builtin_amdgcn_mfma_f32_32x32x16_bf16(t1, PKV(T[6], T[7]), od, 0, 0, 0); } while (0)
; #define WBAR(n) do { asm volatile("s_waitcnt vmcnt(" #n ") lgkmcnt(0)" ::: "memory"); __builtin_amdgcn_s_barrier(); asm volatile("" ::: "memory"); } while (0)
; template <int LD> ...
;     ...
;   { const int vo_ = vbo + v1, vt_ = vbt + v1;
;     ot0 = lds_rd128<16384>(pxra); ot1 = lds_rd128<16384 + 1024>(pxra);
;     TRB(trA, 0, vo_, vt_);
;     asm volatile("s_waitcnt lgkmcnt(0)" : "+v"(ot0), "+v"(ot1) :: "memory"); TRW(trA, 0); TRB(trB, 1, vo_, vt_);
;     MB(o[0], trA, ownB0, ownB1, ot0, ot1); TRW(trB, 0); TRB(trA, 2, vo_, vt_);
;     MB(o[1], trB, ownB0, ownB1, ot0, ot1); TRW(trA, 0); TRB(trB, 3, vo_, vt_);
;     MB(o[2], trA, ownB0, ownB1, ot0, ot1); TRW(trB, 0);
;     MB(o[3], trB, ownB0, ownB1, ot0, ot1); }
;   WBAR(0);
;     ...
;   { auto rr = __builtin_amdgcn_permlane32_swap(__float_as_uint(lsum), __float_as_uint(lsum), false, false);
;     lsum = __uint_as_float(rr[0]) + __uint_as_float(rr[1]); }
;   if (hi == 0) xl[wv * 32 + r32] = lsum;
;   __syncthreads();
;   float rli[16];
; #pragma unroll
;   for (int r = 0; r < 16; ++r) { const int cr = crow(r, hi); rli[r] = __builtin_amdgcn_rcpf(xl[wv * 32 + cr] + xl[(wv ^ 1) * 32 + cr]); }
	ds_read_b128 v[72:75], v171 offset:0x4000
	ds_read_b128 v[76:79], v171 offset:0x4400
	v_mfma_f32_32x32x16_bf16 v[48:63], v[80:83], v[140:143], v[48:63]
	ds_read_b64_tr_b16 v[80:81], v177 offset:0
	ds_read_b64_tr_b16 v[82:83], v177 offset:0x800
	ds_read_b64_tr_b16 v[84:85], v177 offset:0x1000
	ds_read_b64_tr_b16 v[86:87], v177 offset:0x1800
	ds_read_b64_tr_b16 v[88:89], v160 offset:0
	ds_read_b64_tr_b16 v[90:91], v160 offset:0x800
	ds_read_b64_tr_b16 v[92:93], v160 offset:0x1000
	ds_read_b64_tr_b16 v[94:95], v160 offset:0x1800
	s_nop 0
	s_nop 0
	s_waitcnt lgkmcnt(6)
	v_mfma_f32_32x32x16_bf16 v[48:63], v[64:67], v[80:83], v[48:63]
	ds_read_b64_tr_b16 v[80:81], v177 offset:0x200
	ds_read_b64_tr_b16 v[82:83], v177 offset:0xa00
	s_waitcnt lgkmcnt(6)
	v_mfma_f32_32x32x16_bf16 v[48:63], v[68:71], v[84:87], v[48:63]
	ds_read_b64_tr_b16 v[84:85], v177 offset:0x1200
	ds_read_b64_tr_b16 v[86:87], v177 offset:0x1a00
	s_waitcnt lgkmcnt(6)
	v_mfma_f32_32x32x16_bf16 v[48:63], v[72:75], v[88:91], v[48:63]
	ds_read_b64_tr_b16 v[88:89], v160 offset:0x200
	ds_read_b64_tr_b16 v[90:91], v160 offset:0xa00
	ds_read_b64_tr_b16 v[96:97], v160 offset:0x1200
	ds_read_b64_tr_b16 v[98:99], v160 offset:0x1a00
	s_nop 0
	s_nop 0
	s_waitcnt lgkmcnt(6)
	v_mfma_f32_32x32x16_bf16 v[32:47], v[64:67], v[80:83], v[32:47]
	ds_read_b64_tr_b16 v[80:81], v177 offset:0x400
	ds_read_b64_tr_b16 v[82:83], v177 offset:0xc00
	s_waitcnt lgkmcnt(6)
	v_mfma_f32_32x32x16_bf16 v[32:47], v[68:71], v[84:87], v[32:47]
	ds_read_b64_tr_b16 v[84:85], v177 offset:0x1400
	ds_read_b64_tr_b16 v[86:87], v177 offset:0x1c00
	s_waitcnt lgkmcnt(6)
	v_mfma_f32_32x32x16_bf16 v[32:47], v[72:75], v[88:91], v[32:47]
	ds_read_b64_tr_b16 v[88:89], v160 offset:0x400
	ds_read_b64_tr_b16 v[90:91], v160 offset:0xc00
	v_mfma_f32_32x32x16_bf16 v[48:63], v[76:79], v[92:95], v[48:63]
	ds_read_b64_tr_b16 v[92:93], v160 offset:0x1400
	ds_read_b64_tr_b16 v[94:95], v160 offset:0x1c00
	s_nop 0
	s_nop 0
	s_waitcnt lgkmcnt(6)
	v_mfma_f32_32x32x16_bf16 v[16:31], v[64:67], v[80:83], v[16:31]
	v_add_f32_e32 v80, v170, v104
	v_add_f32_e32 v104, v105, v80
	ds_read_b64_tr_b16 v[80:81], v177 offset:0x600
	ds_read_b64_tr_b16 v[82:83], v177 offset:0xe00
	s_waitcnt lgkmcnt(6)
	v_mfma_f32_32x32x16_bf16 v[16:31], v[68:71], v[84:87], v[16:31]
	ds_read_b64_tr_b16 v[84:85], v177 offset:0x1600
	ds_read_b64_tr_b16 v[86:87], v177 offset:0x1e00
	s_waitcnt lgkmcnt(6)
	v_mfma_f32_32x32x16_bf16 v[16:31], v[72:75], v[88:91], v[16:31]
	ds_read_b64_tr_b16 v[88:89], v160 offset:0x600
	ds_read_b64_tr_b16 v[90:91], v160 offset:0xe00
	v_mfma_f32_32x32x16_bf16 v[32:47], v[76:79], v[96:99], v[32:47]
	ds_read_b64_tr_b16 v[96:97], v160 offset:0x1600
	ds_read_b64_tr_b16 v[98:99], v160 offset:0x1e00
	s_nop 0
	s_waitcnt vmcnt(0) lgkmcnt(0)
	s_barrier
	v_mfma_f32_32x32x16_bf16 v[0:15], v[64:67], v[80:83], v[0:15]
	v_add_f32_e32 v64, v106, v104
	v_add_f32_e32 v64, v107, v64
	v_add_f32_e32 v64, v108, v64
	v_add_f32_e32 v64, v109, v64
	v_add_f32_e32 v64, v110, v64
	v_add_f32_e32 v64, v111, v64
	v_add_f32_e32 v64, v112, v64
	v_mfma_f32_32x32x16_bf16 v[0:15], v[68:71], v[84:87], v[0:15]
	v_add_f32_e32 v64, v113, v64
	v_add_f32_e32 v64, v114, v64
	v_add_f32_e32 v64, v115, v64
	v_add_f32_e32 v64, v100, v64
	v_add_f32_e32 v64, v101, v64
	v_add_f32_e32 v64, v102, v64
	v_add_f32_e32 v64, v103, v64
	v_mfma_f32_32x32x16_bf16 v[0:15], v[72:75], v[88:91], v[0:15]
	v_mov_b32_e32 v65, v64
	s_nop 1
	v_permlane32_swap_b32_e32 v64, v65
	v_mfma_f32_32x32x16_bf16 v[16:31], v[76:79], v[92:95], v[16:31]
	v_mfma_f32_32x32x16_bf16 v[0:15], v[76:79], v[96:99], v[0:15]
	s_and_saveexec_b64 s[52:53], vcc
	v_lshl_add_u32 v66, v150, 2, s38
	v_add_f32_e32 v64, v64, v65
	ds_write_b32 v66, v64
	s_or_b64 exec, exec, s[52:53]
	v_add_u32_e32 v92, s38, v178
	v_add_u32_e32 v93, s39, v178
	s_waitcnt vmcnt(0) lgkmcnt(0)
	s_barrier
	ds_read_b128 v[64:67], v92
	ds_read_b128 v[68:71], v92 offset:32
	ds_read_b128 v[72:75], v93
	ds_read_b128 v[76:79], v93 offset:32
	v_ashrrev_i32_e32 v151, 31, v150
	v_lshl_add_u64 v[96:97], v[150:151], 4, s[8:9]
	s_mov_b64 s[52:53], -1
	s_waitcnt lgkmcnt(1)
	v_add_f32_e32 v64, v64, v72
	v_rcp_f32_e32 v80, v64
	v_add_f32_e32 v64, v65, v73
	v_rcp_f32_e32 v81, v64
	v_add_f32_e32 v64, v66, v74
	v_rcp_f32_e32 v82, v64
	v_add_f32_e32 v64, v67, v75
	v_rcp_f32_e32 v83, v64
	s_waitcnt lgkmcnt(0)
	v_add_f32_e32 v64, v68, v76
	v_rcp_f32_e32 v84, v64
	v_add_f32_e32 v64, v69, v77
	v_rcp_f32_e32 v85, v64
	v_add_f32_e32 v64, v70, v78
	v_rcp_f32_e32 v86, v64
	v_add_f32_e32 v64, v71, v79
	v_rcp_f32_e32 v87, v64
	ds_read_b128 v[64:67], v92 offset:64
	ds_read_b128 v[68:71], v93 offset:64
	s_and_b64 vcc, exec, s[2:3]
	s_waitcnt lgkmcnt(0)
	v_add_f32_e32 v64, v64, v68
	v_rcp_f32_e32 v88, v64
	v_add_f32_e32 v64, v65, v69
	v_rcp_f32_e32 v89, v64
	v_add_f32_e32 v64, v66, v70
	v_rcp_f32_e32 v90, v64
	v_add_f32_e32 v64, v67, v71
	v_rcp_f32_e32 v91, v64
	ds_read_b128 v[64:67], v92 offset:96
	ds_read_b128 v[68:71], v93 offset:96
	s_waitcnt lgkmcnt(0)
	v_add_f32_e32 v64, v64, v68
	v_rcp_f32_e32 v92, v64
	v_add_f32_e32 v64, v65, v69
	v_rcp_f32_e32 v93, v64
	v_add_f32_e32 v64, v66, v70
	v_rcp_f32_e32 v94, v64
	v_add_f32_e32 v64, v67, v71
	v_rcp_f32_e32 v95, v64
	s_cbranch_vccz .LBB0_29
; template <int LD> ...
;     ...
;   float ss[16];
; #pragma unroll
;   for (int r = 0; r < 16; ++r) ss[r] = 0.f;
; #pragma unroll
;   for (int d0 = 0; d0 < 4; ++d0)
; #pragma unroll
;     for (int q4 = 0; q4 < 2; ++q4) { const u32x4 w = st[(d0 * 2 + q4) * 64];
; #pragma unroll
;       for (int e = 0; e < 4; ++e) { const unsigned u = w[e]; const int q = 4 * q4 + e;
;         const float da = __uint_as_float(u << 16) - epi.lam * (o[d0][2 * q] * rli[2 * q]);
;         const float db = __uint_as_float(u & 0xffff0000u) - epi.lam * (o[d0][2 * q + 1] * rli[2 * q + 1]);
;         o[d0][2 * q] = da; o[d0][2 * q + 1] = db; ss[2 * q] += da * da; ss[2 * q + 1] += db * db; } }
	global_load_dwordx4 v[182:185], v[96:97], off
	global_load_dwordx4 v[186:189], v[96:97], off offset:1024
	global_load_dwordx4 v[190:193], v[96:97], off offset:2048
	global_load_dwordx4 v[194:197], v[96:97], off offset:3072
	v_add_co_u32_e32 v122, vcc, s56, v96
	v_pk_mul_f32 v[120:121], v[50:51], v[82:83]
	s_nop 0
	v_addc_co_u32_e32 v123, vcc, 0, v97, vcc
	global_load_dwordx4 v[198:201], v[122:123], off
	global_load_dwordx4 v[220:223], v[122:123], off offset:1024
	global_load_dwordx4 v[224:227], v[122:123], off offset:2048
	global_load_dwordx4 v[228:231], v[122:123], off offset:3072
	v_pk_mul_f32 v[168:169], v[34:35], v[82:83]
	v_pk_mul_f32 v[140:141], v[54:55], v[86:87]
	v_pk_mul_f32 v[156:157], v[38:39], v[86:87]
	v_pk_mul_f32 v[136:137], v[42:43], v[90:91]
	v_pk_mul_f32 v[116:117], v[58:59], v[90:91]
	v_pk_mul_f32 v[146:147], v[40:41], v[88:89]
	v_pk_mul_f32 v[152:153], v[52:53], v[84:85]
	v_pk_mul_f32 v[172:173], v[36:37], v[84:85]
	v_pk_mul_f32 v[100:101], v[62:63], v[94:95]
	v_pk_mul_f32 v[112:113], v[46:47], v[94:95]
	v_pk_mul_f32 v[104:105], v[60:61], v[92:93]
	v_pk_mul_f32 v[114:115], v[32:33], v[80:81]
	v_pk_mul_f32 v[128:129], v[44:45], v[92:93]
	v_pk_mul_f32 v[106:107], v[48:49], v[80:81]
	v_pk_mul_f32 v[130:131], v[56:57], v[88:89]
	v_cmp_eq_u32_e32 vcc, 0, v215
	s_waitcnt vmcnt(7)
	v_lshlrev_b32_e32 v64, 16, v182
	v_and_b32_e32 v65, 0xffff0000, v182
	v_lshlrev_b32_e32 v118, 16, v183
	v_and_b32_e32 v119, 0xffff0000, v183
	v_lshlrev_b32_e32 v150, 16, v184
	v_and_b32_e32 v151, 0xffff0000, v184
	v_lshlrev_b32_e32 v138, 16, v185
	v_and_b32_e32 v139, 0xffff0000, v185
	v_pk_fma_f32 v[118:119], v[148:149], v[120:121], v[118:119] neg_lo:[1,0,0] neg_hi:[1,0,0]
	v_pk_fma_f32 v[138:139], v[148:149], v[140:141], v[138:139] neg_lo:[1,0,0] neg_hi:[1,0,0]
	v_pk_fma_f32 v[150:151], v[148:149], v[152:153], v[150:151] neg_lo:[1,0,0] neg_hi:[1,0,0]
	v_pk_fma_f32 v[106:107], v[148:149], v[106:107], v[64:65] neg_lo:[1,0,0] neg_hi:[1,0,0]
	s_waitcnt vmcnt(6)
	v_lshlrev_b32_e32 v76, 16, v186
	v_and_b32_e32 v77, 0xffff0000, v186
	v_lshlrev_b32_e32 v78, 16, v187
	v_and_b32_e32 v79, 0xffff0000, v187
	v_lshlrev_b32_e32 v102, 16, v188
	v_and_b32_e32 v103, 0xffff0000, v188
	v_lshlrev_b32_e32 v98, 16, v189
	v_and_b32_e32 v99, 0xffff0000, v189
	v_pk_fma_f32 v[116:117], v[148:149], v[116:117], v[78:79] neg_lo:[1,0,0] neg_hi:[1,0,0]
	v_pk_fma_f32 v[98:99], v[148:149], v[100:101], v[98:99] neg_lo:[1,0,0] neg_hi:[1,0,0]
	v_pk_fma_f32 v[102:103], v[148:149], v[104:105], v[102:103] neg_lo:[1,0,0] neg_hi:[1,0,0]
	v_pk_fma_f32 v[130:131], v[148:149], v[130:131], v[76:77] neg_lo:[1,0,0] neg_hi:[1,0,0]
	s_waitcnt vmcnt(5)
	v_lshlrev_b32_e32 v108, 16, v190
	v_and_b32_e32 v109, 0xffff0000, v190
	v_lshlrev_b32_e32 v166, 16, v191
	v_and_b32_e32 v167, 0xffff0000, v191
	v_lshlrev_b32_e32 v170, 16, v192
	v_and_b32_e32 v171, 0xffff0000, v192
	v_lshlrev_b32_e32 v154, 16, v193
	v_and_b32_e32 v155, 0xffff0000, v193
	v_pk_fma_f32 v[120:121], v[148:149], v[168:169], v[166:167] neg_lo:[1,0,0] neg_hi:[1,0,0]
	v_pk_fma_f32 v[140:141], v[148:149], v[156:157], v[154:155] neg_lo:[1,0,0] neg_hi:[1,0,0]
	v_pk_mul_f32 v[166:167], v[120:121], v[120:121]
	v_pk_mul_f32 v[154:155], v[140:141], v[140:141]
	v_pk_fma_f32 v[168:169], v[118:119], v[118:119], v[166:167]
	v_pk_mul_f32 v[166:167], v[18:19], v[82:83]
	v_pk_fma_f32 v[156:157], v[138:139], v[138:139], v[154:155]
	v_pk_mul_f32 v[154:155], v[22:23], v[86:87]
	v_pk_fma_f32 v[152:153], v[148:149], v[172:173], v[170:171] neg_lo:[1,0,0] neg_hi:[1,0,0]
	v_pk_fma_f32 v[108:109], v[148:149], v[114:115], v[108:109] neg_lo:[1,0,0] neg_hi:[1,0,0]
	v_pk_mul_f32 v[114:115], v[16:17], v[80:81]
	v_pk_mul_f32 v[64:65], v[108:109], v[108:109]
	v_pk_mul_f32 v[170:171], v[20:21], v[84:85]
	v_pk_fma_f32 v[64:65], v[106:107], v[106:107], v[64:65]
	s_waitcnt vmcnt(4)
	v_lshlrev_b32_e32 v144, 16, v194
	v_and_b32_e32 v145, 0xffff0000, v194
	v_lshlrev_b32_e32 v134, 16, v195
	v_and_b32_e32 v135, 0xffff0000, v195
	v_lshlrev_b32_e32 v126, 16, v196
	v_and_b32_e32 v127, 0xffff0000, v196
	v_lshlrev_b32_e32 v110, 16, v197
	v_and_b32_e32 v111, 0xffff0000, v197
	v_pk_fma_f32 v[134:135], v[148:149], v[136:137], v[134:135] neg_lo:[1,0,0] neg_hi:[1,0,0]
	v_pk_fma_f32 v[144:145], v[148:149], v[146:147], v[144:145] neg_lo:[1,0,0] neg_hi:[1,0,0]
	v_pk_mul_f32 v[146:147], v[24:25], v[88:89]
	v_pk_mul_f32 v[78:79], v[134:135], v[134:135]
	v_pk_mul_f32 v[136:137], v[26:27], v[90:91]
	v_pk_fma_f32 v[78:79], v[116:117], v[116:117], v[78:79]
	v_pk_fma_f32 v[100:101], v[148:149], v[112:113], v[110:111] neg_lo:[1,0,0] neg_hi:[1,0,0]
	v_pk_fma_f32 v[104:105], v[148:149], v[128:129], v[126:127] neg_lo:[1,0,0] neg_hi:[1,0,0]
	v_pk_mul_f32 v[110:111], v[100:101], v[100:101]
	v_pk_mul_f32 v[76:77], v[144:145], v[144:145]
	v_pk_fma_f32 v[112:113], v[98:99], v[98:99], v[110:111]
	v_pk_mul_f32 v[110:111], v[30:31], v[94:95]
	v_pk_mul_f32 v[126:127], v[28:29], v[92:93]
	v_pk_fma_f32 v[76:77], v[130:131], v[130:131], v[76:77]
	s_waitcnt vmcnt(3)
	v_lshlrev_b32_e32 v176, 16, v200
	v_and_b32_e32 v177, 0xffff0000, v200
	v_lshlrev_b32_e32 v174, 16, v201
	v_and_b32_e32 v175, 0xffff0000, v201
	v_lshlrev_b32_e32 v180, 16, v198
	v_and_b32_e32 v181, 0xffff0000, v198
	v_lshlrev_b32_e32 v66, 16, v199
	v_and_b32_e32 v67, 0xffff0000, v199
	v_pk_fma_f32 v[166:167], v[148:149], v[166:167], v[66:67] neg_lo:[1,0,0] neg_hi:[1,0,0]
	v_pk_fma_f32 v[154:155], v[148:149], v[154:155], v[174:175] neg_lo:[1,0,0] neg_hi:[1,0,0]
	v_pk_fma_f32 v[66:67], v[166:167], v[166:167], v[168:169]
	v_pk_mul_f32 v[168:169], v[2:3], v[82:83]
	v_pk_fma_f32 v[174:175], v[154:155], v[154:155], v[156:157]
	v_pk_mul_f32 v[156:157], v[6:7], v[86:87]
	v_pk_fma_f32 v[114:115], v[148:149], v[114:115], v[180:181] neg_lo:[1,0,0] neg_hi:[1,0,0]
	v_pk_mul_f32 v[180:181], v[0:1], v[80:81]
	v_pk_fma_f32 v[170:171], v[148:149], v[170:171], v[176:177] neg_lo:[1,0,0] neg_hi:[1,0,0]
	v_pk_mul_f32 v[176:177], v[4:5], v[84:85]
	v_pk_fma_f32 v[64:65], v[114:115], v[114:115], v[64:65]
	s_waitcnt vmcnt(2)
; template <int X> __device__ __forceinline__ float swz_xor(float v) { return __int_as_float(__builtin_amdgcn_ds_swizzle(__float_as_int(v), (X << 10) | 0x1f)); }
; template <int LD> ...
;     ...
;     for (int q4 = 0; q4 < 2; ++q4) { const u32x4 w = st[(d0 * 2 + q4) * 64];
; #pragma unroll
;       for (int e = 0; e < 4; ++e) { const unsigned u = w[e]; const int q = 4 * q4 + e;
;         const float da = __uint_as_float(u << 16) - epi.lam * (o[d0][2 * q] * rli[2 * q]);
;         const float db = __uint_as_float(u & 0xffff0000u) - epi.lam * (o[d0][2 * q + 1] * rli[2 * q + 1]);
;         o[d0][2 * q] = da; o[d0][2 * q + 1] = db; ss[2 * q] += da * da; ss[2 * q + 1] += db * db; } }
; #pragma unroll
;   for (int r = 0; r < 16; ++r) { ss[r] += swz_xor<1>(ss[r]); ss[r] += swz_xor<2>(ss[r]); ss[r] += swz_xor<4>(ss[r]); ss[r] += swz_xor<8>(ss[r]); ss[r] += swz_xor<16>(ss[r]); }
	v_lshlrev_b32_e32 v158, 16, v220
	v_and_b32_e32 v159, 0xffff0000, v220
	v_lshlrev_b32_e32 v142, 16, v221
	v_and_b32_e32 v143, 0xffff0000, v221
	v_lshlrev_b32_e32 v132, 16, v222
	v_and_b32_e32 v133, 0xffff0000, v222
	v_lshlrev_b32_e32 v124, 16, v223
	v_and_b32_e32 v125, 0xffff0000, v223
	v_pk_fma_f32 v[146:147], v[148:149], v[146:147], v[158:159] neg_lo:[1,0,0] neg_hi:[1,0,0]
	v_pk_fma_f32 v[136:137], v[148:149], v[136:137], v[142:143] neg_lo:[1,0,0] neg_hi:[1,0,0]
	v_pk_mul_f32 v[142:143], v[10:11], v[90:91]
	v_pk_fma_f32 v[78:79], v[136:137], v[136:137], v[78:79]
	v_pk_fma_f32 v[110:111], v[148:149], v[110:111], v[124:125] neg_lo:[1,0,0] neg_hi:[1,0,0]
	v_pk_fma_f32 v[126:127], v[148:149], v[126:127], v[132:133] neg_lo:[1,0,0] neg_hi:[1,0,0]
	v_pk_mul_f32 v[132:133], v[12:13], v[92:93]
	v_pk_fma_f32 v[124:125], v[110:111], v[110:111], v[112:113]
	v_pk_mul_f32 v[112:113], v[14:15], v[94:95]
	v_pk_fma_f32 v[76:77], v[146:147], v[146:147], v[76:77]
	s_waitcnt vmcnt(1)
	v_lshlrev_b32_e32 v122, 16, v224
	v_and_b32_e32 v123, 0xffff0000, v224
	v_lshlrev_b32_e32 v72, 16, v225
	v_and_b32_e32 v73, 0xffff0000, v225
	s_waitcnt vmcnt(0)
	v_lshlrev_b32_e32 v158, 16, v228
	v_and_b32_e32 v159, 0xffff0000, v228
	v_lshlrev_b32_e32 v68, 16, v229
	v_and_b32_e32 v69, 0xffff0000, v229
	v_pk_fma_f32 v[168:169], v[148:149], v[168:169], v[72:73] neg_lo:[1,0,0] neg_hi:[1,0,0]
	v_lshlrev_b32_e32 v172, 16, v226
	v_and_b32_e32 v173, 0xffff0000, v226
	v_lshlrev_b32_e32 v74, 16, v227
	v_and_b32_e32 v75, 0xffff0000, v227
	v_pk_fma_f32 v[142:143], v[148:149], v[142:143], v[68:69] neg_lo:[1,0,0] neg_hi:[1,0,0]
	v_pk_fma_f32 v[66:67], v[168:169], v[168:169], v[66:67]
	v_pk_fma_f32 v[156:157], v[148:149], v[156:157], v[74:75] neg_lo:[1,0,0] neg_hi:[1,0,0]
	v_pk_fma_f32 v[68:69], v[142:143], v[142:143], v[78:79]
	ds_swizzle_b32 v72, v66 offset:swizzle(SWAP,1)
	ds_swizzle_b32 v73, v67 offset:swizzle(SWAP,1)
	v_pk_fma_f32 v[74:75], v[156:157], v[156:157], v[174:175]
	ds_swizzle_b32 v78, v68 offset:swizzle(SWAP,1)
	ds_swizzle_b32 v79, v69 offset:swizzle(SWAP,1)
	ds_swizzle_b32 v174, v74 offset:swizzle(SWAP,1)
	ds_swizzle_b32 v175, v75 offset:swizzle(SWAP,1)
	s_waitcnt lgkmcnt(4)
	v_pk_add_f32 v[66:67], v[66:67], v[72:73]
	ds_swizzle_b32 v72, v66 offset:swizzle(SWAP,2)
	s_waitcnt lgkmcnt(3)
	v_pk_add_f32 v[68:69], v[68:69], v[78:79]
	ds_swizzle_b32 v73, v67 offset:swizzle(SWAP,2)
	s_waitcnt lgkmcnt(2)
	v_pk_add_f32 v[74:75], v[74:75], v[174:175]
	ds_swizzle_b32 v78, v68 offset:swizzle(SWAP,2)
	ds_swizzle_b32 v79, v69 offset:swizzle(SWAP,2)
	ds_swizzle_b32 v174, v74 offset:swizzle(SWAP,2)
	ds_swizzle_b32 v175, v75 offset:swizzle(SWAP,2)
	s_waitcnt lgkmcnt(4)
	v_pk_add_f32 v[66:67], v[66:67], v[72:73]
	ds_swizzle_b32 v72, v66 offset:swizzle(SWAP,4)
	s_waitcnt lgkmcnt(3)
	v_pk_add_f32 v[68:69], v[68:69], v[78:79]
	ds_swizzle_b32 v73, v67 offset:swizzle(SWAP,4)
	s_waitcnt lgkmcnt(2)
	v_pk_add_f32 v[74:75], v[74:75], v[174:175]
	ds_swizzle_b32 v78, v68 offset:swizzle(SWAP,4)
	ds_swizzle_b32 v79, v69 offset:swizzle(SWAP,4)
	ds_swizzle_b32 v174, v74 offset:swizzle(SWAP,4)
	ds_swizzle_b32 v175, v75 offset:swizzle(SWAP,4)
	s_waitcnt lgkmcnt(4)
	v_pk_add_f32 v[66:67], v[66:67], v[72:73]
	ds_swizzle_b32 v72, v66 offset:swizzle(SWAP,8)
	s_waitcnt lgkmcnt(3)
	v_pk_add_f32 v[68:69], v[68:69], v[78:79]
	ds_swizzle_b32 v73, v67 offset:swizzle(SWAP,8)
	s_waitcnt lgkmcnt(2)
	v_pk_add_f32 v[74:75], v[74:75], v[174:175]
	ds_swizzle_b32 v78, v68 offset:swizzle(SWAP,8)
	ds_swizzle_b32 v79, v69 offset:swizzle(SWAP,8)
	ds_swizzle_b32 v174, v74 offset:swizzle(SWAP,8)
	ds_swizzle_b32 v175, v75 offset:swizzle(SWAP,8)
	s_waitcnt lgkmcnt(4)
	v_pk_add_f32 v[66:67], v[66:67], v[72:73]
	ds_swizzle_b32 v72, v66 offset:swizzle(SWAP,16)
	s_waitcnt lgkmcnt(3)
	v_pk_add_f32 v[68:69], v[68:69], v[78:79]
	ds_swizzle_b32 v73, v67 offset:swizzle(SWAP,16)
	s_waitcnt lgkmcnt(2)
	v_pk_add_f32 v[74:75], v[74:75], v[174:175]
	ds_swizzle_b32 v78, v68 offset:swizzle(SWAP,16)
	ds_swizzle_b32 v79, v69 offset:swizzle(SWAP,16)
	ds_swizzle_b32 v174, v74 offset:swizzle(SWAP,16)
	ds_swizzle_b32 v175, v75 offset:swizzle(SWAP,16)
	s_waitcnt lgkmcnt(4)
	v_pk_add_f32 v[66:67], v[66:67], v[72:73]
	v_pk_mul_f32 v[72:73], v[152:153], v[152:153]
	s_waitcnt lgkmcnt(2)
	v_pk_add_f32 v[78:79], v[68:69], v[78:79]
	v_pk_mul_f32 v[68:69], v[104:105], v[104:105]
	v_pk_fma_f32 v[72:73], v[150:151], v[150:151], v[72:73]
	s_waitcnt lgkmcnt(0)
; template <int X> __device__ __forceinline__ float swz_xor(float v) { return __int_as_float(__builtin_amdgcn_ds_swizzle(__float_as_int(v), (X << 10) | 0x1f)); }
; __device__ __forceinline__ int crow(int r, int hi) { return (r & 3) + 8 * (r >> 2) + 4 * hi; }
; template <int LD> ...
;     ...
;     for (int q4 = 0; q4 < 2; ++q4) { const u32x4 w = st[(d0 * 2 + q4) * 64];
; #pragma unroll
;       for (int e = 0; e < 4; ++e) { const unsigned u = w[e]; const int q = 4 * q4 + e;
;         const float da = __uint_as_float(u << 16) - epi.lam * (o[d0][2 * q] * rli[2 * q]);
;         const float db = __uint_as_float(u & 0xffff0000u) - epi.lam * (o[d0][2 * q + 1] * rli[2 * q + 1]);
;         o[d0][2 * q] = da; o[d0][2 * q + 1] = db; ss[2 * q] += da * da; ss[2 * q + 1] += db * db; } }
; #pragma unroll
;   for (int r = 0; r < 16; ++r) { ss[r] += swz_xor<1>(ss[r]); ss[r] += swz_xor<2>(ss[r]); ss[r] += swz_xor<4>(ss[r]); ss[r] += swz_xor<8>(ss[r]); ss[r] += swz_xor<16>(ss[r]); }
;   if (r32 == 0) {
; #pragma unroll
;     for (int r = 0; r < 16; ++r) xs[wv * 32 + crow(r, hi)] = ss[r]; }
	v_pk_add_f32 v[74:75], v[74:75], v[174:175]
	v_pk_mul_f32 v[174:175], v[8:9], v[88:89]
	v_pk_fma_f32 v[68:69], v[102:103], v[102:103], v[68:69]
	v_lshlrev_b32_e32 v128, 16, v230
	v_and_b32_e32 v129, 0xffff0000, v230
	v_lshlrev_b32_e32 v70, 16, v231
	v_and_b32_e32 v71, 0xffff0000, v231
	v_pk_fma_f32 v[122:123], v[148:149], v[180:181], v[122:123] neg_lo:[1,0,0] neg_hi:[1,0,0]
	v_pk_fma_f32 v[72:73], v[170:171], v[170:171], v[72:73]
	v_pk_fma_f32 v[172:173], v[148:149], v[176:177], v[172:173] neg_lo:[1,0,0] neg_hi:[1,0,0]
	v_pk_fma_f32 v[158:159], v[148:149], v[174:175], v[158:159] neg_lo:[1,0,0] neg_hi:[1,0,0]
	v_pk_fma_f32 v[68:69], v[126:127], v[126:127], v[68:69]
	v_pk_fma_f32 v[128:129], v[148:149], v[132:133], v[128:129] neg_lo:[1,0,0] neg_hi:[1,0,0]
	v_pk_fma_f32 v[112:113], v[148:149], v[112:113], v[70:71] neg_lo:[1,0,0] neg_hi:[1,0,0]
	v_pk_fma_f32 v[64:65], v[122:123], v[122:123], v[64:65]
	v_pk_fma_f32 v[72:73], v[172:173], v[172:173], v[72:73]
	v_pk_fma_f32 v[76:77], v[158:159], v[158:159], v[76:77]
	v_pk_fma_f32 v[68:69], v[128:129], v[128:129], v[68:69]
	v_pk_fma_f32 v[70:71], v[112:113], v[112:113], v[124:125]
	ds_swizzle_b32 v180, v64 offset:swizzle(SWAP,1)
	ds_swizzle_b32 v181, v65 offset:swizzle(SWAP,1)
	ds_swizzle_b32 v176, v72 offset:swizzle(SWAP,1)
	ds_swizzle_b32 v177, v73 offset:swizzle(SWAP,1)
	ds_swizzle_b32 v174, v76 offset:swizzle(SWAP,1)
	ds_swizzle_b32 v175, v77 offset:swizzle(SWAP,1)
	ds_swizzle_b32 v132, v68 offset:swizzle(SWAP,1)
	ds_swizzle_b32 v133, v69 offset:swizzle(SWAP,1)
	ds_swizzle_b32 v124, v70 offset:swizzle(SWAP,1)
	ds_swizzle_b32 v125, v71 offset:swizzle(SWAP,1)
	s_waitcnt lgkmcnt(8)
	v_pk_add_f32 v[64:65], v[64:65], v[180:181]
	s_waitcnt lgkmcnt(6)
	v_pk_add_f32 v[72:73], v[72:73], v[176:177]
	s_waitcnt lgkmcnt(4)
	v_pk_add_f32 v[76:77], v[76:77], v[174:175]
	s_waitcnt lgkmcnt(2)
	v_pk_add_f32 v[68:69], v[68:69], v[132:133]
	s_waitcnt lgkmcnt(0)
	v_pk_add_f32 v[70:71], v[70:71], v[124:125]
	ds_swizzle_b32 v180, v64 offset:swizzle(SWAP,2)
	ds_swizzle_b32 v181, v65 offset:swizzle(SWAP,2)
	ds_swizzle_b32 v176, v72 offset:swizzle(SWAP,2)
	ds_swizzle_b32 v177, v73 offset:swizzle(SWAP,2)
	ds_swizzle_b32 v174, v76 offset:swizzle(SWAP,2)
	ds_swizzle_b32 v175, v77 offset:swizzle(SWAP,2)
	ds_swizzle_b32 v132, v68 offset:swizzle(SWAP,2)
	ds_swizzle_b32 v133, v69 offset:swizzle(SWAP,2)
	ds_swizzle_b32 v124, v70 offset:swizzle(SWAP,2)
	ds_swizzle_b32 v125, v71 offset:swizzle(SWAP,2)
	s_waitcnt lgkmcnt(8)
	v_pk_add_f32 v[64:65], v[64:65], v[180:181]
	s_waitcnt lgkmcnt(6)
	v_pk_add_f32 v[72:73], v[72:73], v[176:177]
	s_waitcnt lgkmcnt(4)
	v_pk_add_f32 v[76:77], v[76:77], v[174:175]
	s_waitcnt lgkmcnt(2)
	v_pk_add_f32 v[68:69], v[68:69], v[132:133]
	s_waitcnt lgkmcnt(0)
	v_pk_add_f32 v[70:71], v[70:71], v[124:125]
	ds_swizzle_b32 v180, v64 offset:swizzle(SWAP,4)
	ds_swizzle_b32 v181, v65 offset:swizzle(SWAP,4)
	ds_swizzle_b32 v176, v72 offset:swizzle(SWAP,4)
	ds_swizzle_b32 v177, v73 offset:swizzle(SWAP,4)
	ds_swizzle_b32 v174, v76 offset:swizzle(SWAP,4)
	ds_swizzle_b32 v175, v77 offset:swizzle(SWAP,4)
	ds_swizzle_b32 v132, v68 offset:swizzle(SWAP,4)
	ds_swizzle_b32 v133, v69 offset:swizzle(SWAP,4)
	ds_swizzle_b32 v124, v70 offset:swizzle(SWAP,4)
	ds_swizzle_b32 v125, v71 offset:swizzle(SWAP,4)
	s_waitcnt lgkmcnt(8)
	v_pk_add_f32 v[64:65], v[64:65], v[180:181]
	s_waitcnt lgkmcnt(6)
	v_pk_add_f32 v[72:73], v[72:73], v[176:177]
	s_waitcnt lgkmcnt(4)
	v_pk_add_f32 v[76:77], v[76:77], v[174:175]
	s_waitcnt lgkmcnt(2)
	v_pk_add_f32 v[68:69], v[68:69], v[132:133]
	s_waitcnt lgkmcnt(0)
	v_pk_add_f32 v[70:71], v[70:71], v[124:125]
	ds_swizzle_b32 v180, v64 offset:swizzle(SWAP,8)
	ds_swizzle_b32 v181, v65 offset:swizzle(SWAP,8)
	ds_swizzle_b32 v176, v72 offset:swizzle(SWAP,8)
	ds_swizzle_b32 v177, v73 offset:swizzle(SWAP,8)
	ds_swizzle_b32 v174, v76 offset:swizzle(SWAP,8)
	ds_swizzle_b32 v175, v77 offset:swizzle(SWAP,8)
	ds_swizzle_b32 v132, v68 offset:swizzle(SWAP,8)
	ds_swizzle_b32 v133, v69 offset:swizzle(SWAP,8)
	ds_swizzle_b32 v124, v70 offset:swizzle(SWAP,8)
	ds_swizzle_b32 v125, v71 offset:swizzle(SWAP,8)
	s_waitcnt lgkmcnt(8)
	v_pk_add_f32 v[64:65], v[64:65], v[180:181]
	s_waitcnt lgkmcnt(6)
	v_pk_add_f32 v[72:73], v[72:73], v[176:177]
	s_waitcnt lgkmcnt(4)
	v_pk_add_f32 v[76:77], v[76:77], v[174:175]
	s_waitcnt lgkmcnt(2)
	v_pk_add_f32 v[68:69], v[68:69], v[132:133]
	s_waitcnt lgkmcnt(0)
	v_pk_add_f32 v[70:71], v[70:71], v[124:125]
	ds_swizzle_b32 v180, v64 offset:swizzle(SWAP,16)
	ds_swizzle_b32 v181, v65 offset:swizzle(SWAP,16)
	ds_swizzle_b32 v176, v72 offset:swizzle(SWAP,16)
	ds_swizzle_b32 v177, v73 offset:swizzle(SWAP,16)
	ds_swizzle_b32 v174, v76 offset:swizzle(SWAP,16)
	ds_swizzle_b32 v175, v77 offset:swizzle(SWAP,16)
	ds_swizzle_b32 v132, v68 offset:swizzle(SWAP,16)
	ds_swizzle_b32 v133, v69 offset:swizzle(SWAP,16)
	ds_swizzle_b32 v124, v70 offset:swizzle(SWAP,16)
	ds_swizzle_b32 v125, v71 offset:swizzle(SWAP,16)
	s_waitcnt lgkmcnt(8)
	v_pk_add_f32 v[64:65], v[64:65], v[180:181]
	s_waitcnt lgkmcnt(6)
	v_pk_add_f32 v[72:73], v[72:73], v[176:177]
	s_waitcnt lgkmcnt(4)
	v_pk_add_f32 v[76:77], v[76:77], v[174:175]
	s_waitcnt lgkmcnt(2)
	v_pk_add_f32 v[68:69], v[68:69], v[132:133]
	s_waitcnt lgkmcnt(0)
	v_pk_add_f32 v[70:71], v[70:71], v[124:125]
	s_and_saveexec_b64 s[52:53], vcc
	s_cbranch_execz .LBB0_28
	v_add_u32_e32 v124, s40, v178
	ds_write_b128 v124, v[64:67]
	ds_write_b128 v124, v[72:75] offset:32
	ds_write_b128 v124, v[76:79] offset:64
	ds_write_b128 v124, v[68:71] offset:96
